# no XCD stagger: all norm1 rows done in the chip-wide P1 phase, per-XCC P1b pass skipped
# speedup vs baseline: 1.0122x; 1.0122x over previous
; __global__ void __launch_bounds__(NWAVES * 64, 2) fwd_kernel(Args args_unused) {
;     ...
;         { const int nrow = grouped ? (4 * SEQ + 4 * CTXL) : MT;
;           for (int r = gw; r < nrow; r += NGW) { const int mrow = (!grouped || r < 4 * SEQ) ? r : ML + (r - 4 * SEQ); P1_ROW(mrow); } }
.LBB0_170:
	s_cmp_lt_i32 s89, 2
	s_cselect_b64 s[10:11], -1, 0
	s_and_b64 s[0:1], s[10:11], s[20:21]
	s_andn2_b64 vcc, exec, s[0:1]
	s_cbranch_vccnz .LBB0_183
	v_mbcnt_lo_u32_b32 v128, -1, 0
	v_mbcnt_hi_u32_b32 v128, -1, v128
	s_load_dwordx2 s[12:13], s[96:97], 0xb0
	s_waitcnt lgkmcnt(0)
	s_load_dwordx2 s[4:5], s[96:97], 0
	s_waitcnt lgkmcnt(0)
	s_load_dwordx2 s[6:7], s[96:97], 16
	s_waitcnt lgkmcnt(0)
	s_movk_i32 s3, 0x4400
	s_and_b64 s[0:1], s[18:19], exec
	s_load_dwordx2 s[14:15], s[96:97], 48
	s_waitcnt lgkmcnt(0)
	s_mov_b32 s0, 0x8800
	s_cmp_ge_i32 s22, s0
	s_cbranch_scc1 .LBB0_178
	v_mbcnt_lo_u32_b32 v0, -1, 0
	v_mbcnt_hi_u32_b32 v0, -1, v0
	v_and_b32_e32 v1, 64, v0
	v_add_u32_e32 v1, 64, v1
	v_xor_b32_e32 v2, 1, v0
	v_cmp_lt_i32_e32 vcc, v2, v1
	v_lshlrev_b32_e32 v4, 3, v128
	v_ashrrev_i32_e32 v5, 31, v4
	v_cndmask_b32_e32 v2, v0, v2, vcc
	v_lshlrev_b32_e32 v6, 2, v2
	v_xor_b32_e32 v2, 2, v0
	v_cmp_lt_i32_e32 vcc, v2, v1
	s_mov_b64 s[16:17], 0x2000000
	s_mov_b32 s9, 0
	v_cndmask_b32_e32 v2, v0, v2, vcc
	v_lshlrev_b32_e32 v7, 2, v2
	v_xor_b32_e32 v2, 4, v0
	v_cmp_lt_i32_e32 vcc, v2, v1
	v_mov_b32_e32 v12, 0x358637bd
	s_mov_b32 s1, 0x800000
	v_cndmask_b32_e32 v2, v0, v2, vcc
	v_lshlrev_b32_e32 v8, 2, v2
	v_xor_b32_e32 v2, 8, v0
	v_cmp_lt_i32_e32 vcc, v2, v1
	s_movk_i32 s3, 0x1000
	s_mov_b32 s23, s22
	v_cndmask_b32_e32 v2, v0, v2, vcc
	v_lshlrev_b32_e32 v9, 2, v2
	v_xor_b32_e32 v2, 16, v0
	v_cmp_lt_i32_e32 vcc, v2, v1
	s_nop 1
	v_cndmask_b32_e32 v2, v0, v2, vcc
	v_lshlrev_b32_e32 v10, 2, v2
	v_xor_b32_e32 v2, 32, v0
	v_cmp_lt_i32_e32 vcc, v2, v1
	s_nop 1
	v_cndmask_b32_e32 v0, v0, v2, vcc
	v_lshlrev_b32_e32 v11, 2, v0
	v_lshl_add_u64 v[0:1], v[4:5], 1, s[12:13]
	v_lshl_add_u64 v[0:1], v[0:1], 0, s[16:17]
	v_lshl_add_u64 v[2:3], v[4:5], 2, s[14:15]
	v_lshlrev_b64 v[4:5], 2, v[4:5]
	s_mov_b64 s[14:15], 0x1000
	s_branch .LBB0_174

; __global__ void __launch_bounds__(NWAVES * 64, 2) fwd_kernel(Args args_unused) {
;     ...
;           for (int r = gw; r < nrow; r += NGW) { const int mrow = (!grouped || r < 4 * SEQ) ? r : ML + (r - 4 * SEQ); P1_ROW(mrow); } }
.LBB0_174:
	s_mov_b64 s[16:17], 0
	s_add_i32 s8, s23, 0x4000
	s_and_b64 s[16:17], s[16:17], exec
	s_cselect_b32 s16, s8, s23
	s_cmpk_gt_i32 s16, 0x7fff
	s_mov_b64 s[26:27], -1
	s_cbranch_scc0 .LBB0_176
	s_add_i32 s8, s16, 0xffff8000
	s_lshl_b64 s[20:21], s[8:9], 12
	s_add_u32 s20, s6, s20
	s_addc_u32 s21, s7, s21
	s_mov_b32 s17, s9
	s_mov_b64 s[26:27], 0

; #define LAS __attribute__((address_space(3)))
; #define ARGP(i) ka_ptr(ka, (i) * 8)
; #define ARG_WS() ((unsigned char*)ka_ptr(ka, 176))
; #define GET_LANE() int lane; asm volatile("v_mbcnt_lo_u32_b32 %0, -1, 0\n\tv_mbcnt_hi_u32_b32 %0, -1, %0" : "=v"(lane)); const int tid = wave * 64 + lane; (void)tid;
; __global__ void __launch_bounds__(NWAVES * 64, 2) fwd_kernel(Args args_unused) {
;     ...
;     const int gx = grouped ? (int)xcc : (bx & 7), gl = grouped ? (int)__builtin_amdgcn_readfirstlane(((volatile LAS unsigned*)(lds + LDSCTL_OFF))[2]) : (bx >> 3);
;     const int cv = gl * 8 + gx;
;     const int vcu2 = grouped ? gx * (G >> 3) + gl : vcu;
;     ...
;     if (IN(1) && IN(2) && grouped && gx >= 4) {
;         GET_LANE();
;         unsigned char* const ws = ARG_WS();
;         const float* mod = (const float*)(ws + WS_MOD); bf16_t* Hb = (bf16_t*)(ws + WS_H);
;         const float* x = ARGP(I_X); const float* ctx = ARGP(I_CTX); const float* ng = ARGP(I_N1G);
;         const int nlw = (G >> 3) * NWAVES;
;         for (int r = gl * NWAVES + wave; r < SEQ + CTXL; r += nlw) { const int mrow = (r < SEQ) ? gx * SEQ + r : ML + gx * CTXL + (r - SEQ); P1_ROW(mrow); }
;         grp_barrier((unsigned*)(ARG_WS() + WS_BAR) + XCD_BAR_WORDS, (unsigned)gx, (unsigned)(G >> 3), tid);
;     }
.LBB0_237:
	s_and_b32 s3, s2, 7
	s_and_b64 s[0:1], s[18:19], exec
	s_cselect_b32 s85, s82, s3
	s_lshl_b32 s56, s60, 3
	s_ashr_i32 s94, s33, 3
	s_and_b64 s[0:1], s[6:7], s[18:19]
	s_cmp_gt_u32 s85, 3
	s_cselect_b64 s[6:7], -1, 0
	s_and_b64 s[0:1], s[0:1], s[6:7]
	s_andn2_b64 vcc, exec, s[0:1]
	s_branch .LBB0_267
	v_mbcnt_lo_u32_b32 v6, -1, 0
	v_mbcnt_hi_u32_b32 v6, -1, v6
	s_load_dwordx2 s[6:7], s[96:97], 0xb0
	s_waitcnt lgkmcnt(0)
	s_load_dwordx2 s[8:9], s[96:97], 0
	s_waitcnt lgkmcnt(0)
	s_load_dwordx2 s[10:11], s[96:97], 16
	s_waitcnt lgkmcnt(0)
	s_load_dwordx2 s[14:15], s[96:97], 48
	s_waitcnt lgkmcnt(0)
	s_add_i32 s0, s56, s90
	s_cmpk_gt_i32 s0, 0x10ff
	s_cbranch_scc1 .LBB0_245
	v_mbcnt_lo_u32_b32 v0, -1, 0
	v_mbcnt_hi_u32_b32 v0, -1, v0
	v_and_b32_e32 v1, 64, v0
	v_add_u32_e32 v1, 64, v1
	v_xor_b32_e32 v2, 1, v0
	v_cmp_lt_i32_e32 vcc, v2, v1
	v_lshlrev_b32_e32 v4, 3, v6
	v_ashrrev_i32_e32 v5, 31, v4
	v_cndmask_b32_e32 v2, v0, v2, vcc
	v_lshlrev_b32_e32 v7, 2, v2
	v_xor_b32_e32 v2, 2, v0
	v_cmp_lt_i32_e32 vcc, v2, v1
	s_and_b32 s1, s33, -8
	s_lshl_b32 s3, s82, 8
	v_cndmask_b32_e32 v2, v0, v2, vcc
	v_lshlrev_b32_e32 v8, 2, v2
	v_xor_b32_e32 v2, 4, v0
	v_cmp_lt_i32_e32 vcc, v2, v1
	s_mov_b64 s[16:17], 0x2000000
	s_or_b32 s3, s3, 0x7000
	v_cndmask_b32_e32 v2, v0, v2, vcc
	v_lshlrev_b32_e32 v9, 2, v2
	v_xor_b32_e32 v2, 8, v0
	v_cmp_lt_i32_e32 vcc, v2, v1
	s_lshl_b32 s26, s82, 12
	s_mov_b32 s13, 0
	v_cndmask_b32_e32 v2, v0, v2, vcc
	v_lshlrev_b32_e32 v10, 2, v2
	v_xor_b32_e32 v2, 16, v0
	v_cmp_lt_i32_e32 vcc, v2, v1
	s_ashr_i32 s27, s0, 31
	s_ashr_i32 s28, s1, 31
	v_cndmask_b32_e32 v2, v0, v2, vcc
	v_lshlrev_b32_e32 v11, 2, v2
	v_xor_b32_e32 v2, 32, v0
	v_cmp_lt_i32_e32 vcc, v2, v1
	s_movk_i32 s29, 0x1000
	v_mov_b32_e32 v13, 0x358637bd
	v_cndmask_b32_e32 v0, v0, v2, vcc
	v_lshlrev_b32_e32 v12, 2, v0
	v_lshl_add_u64 v[0:1], v[4:5], 1, s[6:7]
	v_lshl_add_u64 v[0:1], v[0:1], 0, s[16:17]
	v_lshl_add_u64 v[2:3], v[4:5], 2, s[14:15]
	v_lshlrev_b64 v[4:5], 2, v[4:5]
	s_mov_b32 s30, 0x800000
	s_mov_b64 s[14:15], 0x1000
	s_branch .LBB0_241
